# own-block phase merge epilogue: all mask / lse / partial-O loads of a unit issued up front behind one wait (was 17 serialized round trips per unit); exec-masked blocks copy from preloaded registers
# baseline (speedup 1.0000x reference)
; __device__ __forceinline__ int crow(int r,int hi){return (r&3)+8*(r>>2)+4*hi;}
; template<int THRL,int KIND> __device__ __forceinline__ void attn_unit(const bf16*Qlane,const bf16*__restrict__ Kh,const bf16*__restrict__ Vh,const int NT,const int NTs,char*shm,const float*cbh,const unsigned selw_in,const float*relb,const int h,bf16*Odirect,const int pidx,bf16*PO,float*PL,const int ...
;     ...
;   float rli[16];
;   #pragma unroll
;   for(int r=0;r<16;++r)rli[r]=__builtin_amdgcn_rcpf(wsf[32+crow(r,hi)]);
;   typedef __attribute__((address_space(3))) int lds_i32; lds_i32* const dstt=(lds_i32*)(shm3+LDS_CB)+wid*32;
;   if constexpr(KIND==2){ if(hi==0){ dstt[r32]=pidx; if(pidx>=0) PL[pidx]=mhat+__builtin_log2f(l_reg); } }
;   if constexpr(KIND==1){ if(hi==0) wsf[r32]=mhat+__builtin_log2f(l_reg); }
;   { bf16*stg=(bf16*)(shm+LDS_OST)+wid*2048;
;     #pragma unroll
;     for(int r=0;r<16;++r){const int orow=crow(r,hi);
;       #pragma unroll
;       for(int d0=0;d0<2;++d0)stg[orow*64+d0*32+r32]=__float2bfloat16(o[d0][r]*rli[r]);}
;     asm volatile("s_waitcnt lgkmcnt(0)":::"memory");
;     #pragma unroll
;     for(int i=0;i<4;++i){const int row=i*8+(lane>>3),ch=lane&7; const u32x4 v=*(const u32x4*)(stg+row*64+ch*8);
;       if constexpr(KIND==0){ ATTN_STORE16(Odirect+(long)row*DM+ch*8,v); }
;       else if constexpr(KIND==2){ const int d_=dstt[row]; if(d_>=0) ATTN_STORE16(PO+(long)d_*64+ch*8,v); }
;       else { const long ridx=(long)pidx+wid*32+row; const unsigned sm_=((const unsigned*)cbh)[wid*32+row]; const int np=__builtin_popcount(sm_&~(1u<<trel));
;         const f32x4v l4=*(const f32x4v*)(PL+ridx*4); const float l0=wsf[row];
;         float mx=l0; if(np>0)mx=__builtin_fmaxf(mx,l4[1]); if(np>1)mx=__builtin_fmaxf(mx,l4[2]); if(np>2)mx=__builtin_fmaxf(mx,l4[3]);
;         const float w0=__builtin_amdgcn_exp2f(l0-mx); float wsum=w0; float ac[8];
;         ac[0]=w0*__uint_as_float(v[0]<<16); ac[1]=w0*__uint_as_float(v[0]&0xffff0000u); ac[2]=w0*__uint_as_float(v[1]<<16); ac[3]=w0*__uint_as_float(v[1]&0xffff0000u);
;         ac[4]=w0*__uint_as_float(v[2]<<16); ac[5]=w0*__uint_as_float(v[2]&0xffff0000u); ac[6]=w0*__uint_as_float(v[3]<<16); ac[7]=w0*__uint_as_float(v[3]&0xffff0000u);
;         #pragma unroll
;         for(int s_=1;s_<4;++s_) if(s_<=np){ const float ws_=__builtin_amdgcn_exp2f(l4[s_]-mx); wsum+=ws_; const u32x4 p=*(const u32x4*)(PO+(ridx*4+s_)*64+ch*8);
.LBB0_1067:
	s_or_b64 exec, exec, s[40:41]
	s_ashr_i32 s37, s36, 31
	s_lshl_b64 s[8:9], s[36:37], 15
	s_add_u32 s8, s15, s8
	s_waitcnt lgkmcnt(3)
	v_rcp_f32_e32 v44, v44
	s_addc_u32 s9, s16, s9
	s_lshl_b32 s13, s21, 2
	s_add_u32 s38, s8, s13
	s_addc_u32 s39, s9, 0
	s_lshl_b32 s8, s36, 13
	s_lshl_b32 s9, s22, 12
	v_rcp_f32_e32 v45, v45
	s_or_b32 s8, s8, s21
	s_add_i32 s21, s9, 0
	v_lshl_add_u32 v48, v176, 1, s21
	v_mul_f32_e32 v0, v0, v44
	v_lshl_add_u32 v49, v182, 9, v48
	v_cvt_pk_bf16_f32 v0, v0, s0
	ds_write_b16 v49, v0 offset:51200
	v_mul_f32_e32 v0, v16, v44
	v_rcp_f32_e32 v46, v46
	v_cvt_pk_bf16_f32 v0, v0, s0
	v_mul_f32_e32 v1, v1, v45
	ds_write_b16 v49, v0 offset:51264
	v_lshl_add_u32 v0, v183, 7, v48
	v_cvt_pk_bf16_f32 v1, v1, s0
	ds_write_b16 v0, v1 offset:51200
	v_mul_f32_e32 v1, v17, v45
	v_cvt_pk_bf16_f32 v1, v1, s0
	v_rcp_f32_e32 v47, v47
	ds_write_b16 v0, v1 offset:51264
	v_mul_f32_e32 v1, v2, v46
	v_lshl_add_u32 v0, v184, 7, v48
	v_cvt_pk_bf16_f32 v1, v1, s0
	ds_write_b16 v0, v1 offset:51200
	v_mul_f32_e32 v1, v18, v46
	v_cvt_pk_bf16_f32 v1, v1, s0
	s_waitcnt lgkmcnt(7)
	v_rcp_f32_e32 v40, v40
	ds_write_b16 v0, v1 offset:51264
	v_mul_f32_e32 v1, v3, v47
	v_lshl_add_u32 v0, v185, 7, v48
	v_cvt_pk_bf16_f32 v1, v1, s0
	ds_write_b16 v0, v1 offset:51200
	v_mul_f32_e32 v1, v19, v47
	v_cvt_pk_bf16_f32 v1, v1, s0
	v_rcp_f32_e32 v41, v41
	ds_write_b16 v0, v1 offset:51264
	v_mul_f32_e32 v1, v4, v40
	v_lshl_add_u32 v0, v186, 7, v48
	v_cvt_pk_bf16_f32 v1, v1, s0
	ds_write_b16 v0, v1 offset:51200
	v_mul_f32_e32 v1, v20, v40
	v_cvt_pk_bf16_f32 v1, v1, s0
	v_rcp_f32_e32 v42, v42
	ds_write_b16 v0, v1 offset:51264
	v_mul_f32_e32 v1, v5, v41
	v_lshl_add_u32 v0, v187, 7, v48
	v_cvt_pk_bf16_f32 v1, v1, s0
	ds_write_b16 v0, v1 offset:51200
	v_mul_f32_e32 v1, v21, v41
	v_cvt_pk_bf16_f32 v1, v1, s0
	v_rcp_f32_e32 v43, v43
	ds_write_b16 v0, v1 offset:51264
	v_mul_f32_e32 v1, v6, v42
	v_lshl_add_u32 v0, v189, 7, v48
	v_cvt_pk_bf16_f32 v1, v1, s0
	ds_write_b16 v0, v1 offset:51200
	v_mul_f32_e32 v1, v22, v42
	v_cvt_pk_bf16_f32 v1, v1, s0
	s_waitcnt lgkmcnt(14)
	v_rcp_f32_e32 v36, v36
	ds_write_b16 v0, v1 offset:51264
	v_mul_f32_e32 v1, v7, v43
	v_lshl_add_u32 v0, v190, 7, v48
	v_cvt_pk_bf16_f32 v1, v1, s0
	ds_write_b16 v0, v1 offset:51200
	v_mul_f32_e32 v1, v23, v43
	v_cvt_pk_bf16_f32 v1, v1, s0
	v_rcp_f32_e32 v37, v37
	ds_write_b16 v0, v1 offset:51264
	v_mul_f32_e32 v1, v8, v36
	v_lshl_add_u32 v0, v191, 7, v48
	v_cvt_pk_bf16_f32 v1, v1, s0
	ds_write_b16 v0, v1 offset:51200
	v_mul_f32_e32 v1, v24, v36
	v_cvt_pk_bf16_f32 v1, v1, s0
	v_rcp_f32_e32 v38, v38
	ds_write_b16 v0, v1 offset:51264
	v_mul_f32_e32 v1, v9, v37
	v_lshl_add_u32 v0, v192, 7, v48
	v_cvt_pk_bf16_f32 v1, v1, s0
	ds_write_b16 v0, v1 offset:51200
	v_mul_f32_e32 v1, v25, v37
	v_cvt_pk_bf16_f32 v1, v1, s0
	v_rcp_f32_e32 v39, v39
	ds_write_b16 v0, v1 offset:51264
	v_mul_f32_e32 v1, v10, v38
	v_lshl_add_u32 v0, v193, 7, v48
	v_cvt_pk_bf16_f32 v1, v1, s0
	ds_write_b16 v0, v1 offset:51200
	v_mul_f32_e32 v1, v26, v38
	v_cvt_pk_bf16_f32 v1, v1, s0
	s_waitcnt lgkmcnt(14)
	v_rcp_f32_e32 v32, v32
	ds_write_b16 v0, v1 offset:51264
	v_mul_f32_e32 v1, v11, v39
	v_lshl_add_u32 v0, v194, 7, v48
	v_cvt_pk_bf16_f32 v1, v1, s0
	ds_write_b16 v0, v1 offset:51200
	v_mul_f32_e32 v1, v27, v39
	v_cvt_pk_bf16_f32 v1, v1, s0
	v_rcp_f32_e32 v33, v33
	ds_write_b16 v0, v1 offset:51264
	v_mul_f32_e32 v1, v12, v32
	v_lshl_add_u32 v0, v195, 7, v48
	v_cvt_pk_bf16_f32 v1, v1, s0
	ds_write_b16 v0, v1 offset:51200
	v_mul_f32_e32 v1, v28, v32
	v_cvt_pk_bf16_f32 v1, v1, s0
	v_rcp_f32_e32 v34, v34
	ds_write_b16 v0, v1 offset:51264
	v_mul_f32_e32 v1, v13, v33
	v_lshl_add_u32 v0, v196, 7, v48
	v_cvt_pk_bf16_f32 v1, v1, s0
	ds_write_b16 v0, v1 offset:51200
	v_mul_f32_e32 v1, v29, v33
	v_cvt_pk_bf16_f32 v1, v1, s0
	v_rcp_f32_e32 v35, v35
	ds_write_b16 v0, v1 offset:51264
	v_mul_f32_e32 v1, v14, v34
	v_lshl_add_u32 v0, v197, 7, v48
	v_cvt_pk_bf16_f32 v1, v1, s0
	ds_write_b16 v0, v1 offset:51200
	v_mul_f32_e32 v1, v30, v34
	v_cvt_pk_bf16_f32 v1, v1, s0
	ds_write_b16 v0, v1 offset:51264
	v_mul_f32_e32 v1, v15, v35
	v_lshl_add_u32 v0, v198, 7, v48
	v_cvt_pk_bf16_f32 v1, v1, s0
	ds_write_b16 v0, v1 offset:51200
	v_mul_f32_e32 v1, v31, v35
	v_cvt_pk_bf16_f32 v1, v1, s0
	v_lshrrev_b32_e32 v176, 3, v181
	s_ashr_i32 s9, s8, 31
	s_ashr_i32 s13, s12, 31
	ds_write_b16 v0, v1 offset:51264
	s_add_u32 s8, s12, s8
	v_or_b32_e32 v0, s12, v176
	s_addc_u32 s9, s13, s9
	v_ashrrev_i32_e32 v1, 31, v0
	s_waitcnt lgkmcnt(0)
	v_or_b32_e32 v16, s8, v176
	v_mov_b32_e32 v17, s9
	v_lshl_add_u64 v[0:1], v[0:1], 2, s[38:39]
	v_and_b32_e32 v152, 56, v180
	v_lshlrev_b32_e32 v152, 1, v152
	v_mov_b32_e32 v153, v177
	v_lshl_add_u64 v[152:153], s[4:5], 0, v[152:153]
	v_lshlrev_b64 v[154:155], 9, v[16:17]
	v_lshl_add_u64 v[152:153], v[152:153], 0, v[154:155]
	global_load_dwordx4 v[230:233], v[152:153], off offset:128
	global_load_dwordx4 v[234:237], v[152:153], off offset:256
	global_load_dwordx4 v[246:249], v[152:153], off offset:384
	s_mov_b32 s99, 0
	s_movk_i32 s98, 0x1000
	v_lshl_add_u64 v[154:155], v[152:153], 0, s[98:99]
	global_load_dwordx4 v[96:99], v[154:155], off offset:128
	global_load_dwordx4 v[116:119], v[154:155], off offset:256
	global_load_dwordx4 v[120:123], v[154:155], off offset:384
	s_movk_i32 s98, 0x2000
	v_lshl_add_u64 v[154:155], v[152:153], 0, s[98:99]
	global_load_dwordx4 v[124:127], v[154:155], off offset:128
	global_load_dwordx4 v[128:131], v[154:155], off offset:256
	global_load_dwordx4 v[136:139], v[154:155], off offset:384
	s_movk_i32 s98, 0x3000
	v_lshl_add_u64 v[154:155], v[152:153], 0, s[98:99]
	global_load_dwordx4 v[140:143], v[154:155], off offset:128
	global_load_dwordx4 v[144:147], v[154:155], off offset:256
	global_load_dwordx4 v[148:151], v[154:155], off offset:384
	v_lshl_add_u64 v[154:155], v[16:17], 4, s[28:29]
	global_load_dwordx4 v[218:221], v[154:155], off offset:128
	global_load_dwordx4 v[222:225], v[154:155], off offset:256
	global_load_dwordx4 v[226:229], v[154:155], off offset:384
	v_lshl_add_u64 v[154:155], v[176:177], 0, s[12:13]
	v_lshl_add_u64 v[154:155], v[154:155], 2, s[38:39]
	global_load_dword v215, v[154:155], off offset:32
	global_load_dword v216, v[154:155], off offset:64
	global_load_dword v217, v[154:155], off offset:96
	global_load_dword v8, v[0:1], off
	v_lshl_add_u64 v[0:1], v[16:17], 4, s[28:29]
	global_load_dwordx4 v[0:3], v[0:1], off
	s_waitcnt vmcnt(0)
; __device__ __forceinline__ unsigned cvtpk_s(float lo,float hi){f32x2_t v={lo,hi};bf16x2_t b=__builtin_convertvector(v,bf16x2_t);return __builtin_bit_cast(unsigned,b);}
; template<int THRL,int KIND> __device__ __forceinline__ void attn_unit(const bf16*Qlane,const bf16*__restrict__ Kh,const bf16*__restrict__ Vh,const int NT,const int NTs,char*shm,const float*cbh,const unsigned selw_in,const float*relb,const int h,bf16*Odirect,const int pidx,bf16*PO,float*PL,const int ...
;     ...
;     for(int i=0;i<4;++i){const int row=i*8+(lane>>3),ch=lane&7; const u32x4 v=*(const u32x4*)(stg+row*64+ch*8);
;       if constexpr(KIND==0){ ATTN_STORE16(Odirect+(long)row*DM+ch*8,v); }
;       else if constexpr(KIND==2){ const int d_=dstt[row]; if(d_>=0) ATTN_STORE16(PO+(long)d_*64+ch*8,v); }
;       else { const long ridx=(long)pidx+wid*32+row; const unsigned sm_=((const unsigned*)cbh)[wid*32+row]; const int np=__builtin_popcount(sm_&~(1u<<trel));
;         const f32x4v l4=*(const f32x4v*)(PL+ridx*4); const float l0=wsf[row];
;         float mx=l0; if(np>0)mx=__builtin_fmaxf(mx,l4[1]); if(np>1)mx=__builtin_fmaxf(mx,l4[2]); if(np>2)mx=__builtin_fmaxf(mx,l4[3]);
;         const float w0=__builtin_amdgcn_exp2f(l0-mx); float wsum=w0; float ac[8];
;         ac[0]=w0*__uint_as_float(v[0]<<16); ac[1]=w0*__uint_as_float(v[0]&0xffff0000u); ac[2]=w0*__uint_as_float(v[1]<<16); ac[3]=w0*__uint_as_float(v[1]&0xffff0000u);
;         ac[4]=w0*__uint_as_float(v[2]<<16); ac[5]=w0*__uint_as_float(v[2]&0xffff0000u); ac[6]=w0*__uint_as_float(v[3]<<16); ac[7]=w0*__uint_as_float(v[3]&0xffff0000u);
;         #pragma unroll
;         for(int s_=1;s_<4;++s_) if(s_<=np){ const float ws_=__builtin_amdgcn_exp2f(l4[s_]-mx); wsum+=ws_; const u32x4 p=*(const u32x4*)(PO+(ridx*4+s_)*64+ch*8);
;           ac[0]+=ws_*__uint_as_float(p[0]<<16); ac[1]+=ws_*__uint_as_float(p[0]&0xffff0000u); ac[2]+=ws_*__uint_as_float(p[1]<<16); ac[3]+=ws_*__uint_as_float(p[1]&0xffff0000u);
;           ac[4]+=ws_*__uint_as_float(p[2]<<16); ac[5]+=ws_*__uint_as_float(p[2]&0xffff0000u); ac[6]+=ws_*__uint_as_float(p[3]<<16); ac[7]+=ws_*__uint_as_float(p[3]&0xffff0000u); }
;         const float inv=__builtin_amdgcn_rcpf(wsum); u32x4 ov; ov[0]=cvtpk_s(ac[0]*inv,ac[1]*inv); ov[1]=cvtpk_s(ac[2]*inv,ac[3]*inv); ov[2]=cvtpk_s(ac[4]*inv,ac[5]*inv); ov[3]=cvtpk_s(ac[6]*inv,ac[7]*inv);
	v_and_b32_e32 v0, 56, v180
	v_lshlrev_b32_e32 v6, 1, v0
	v_add_u32_e32 v20, s21, v6
	v_lshl_add_u32 v0, v176, 7, v20
	v_lshl_add_u32 v21, v176, 2, s70
	ds_read_b128 v[12:15], v0 offset:51200
	ds_read_b32 v0, v21 offset:49152
	s_lshl_b32 s20, 1, s20
	v_mov_b32_e32 v7, v177
	v_lshl_add_u64 v[4:5], s[4:5], 0, v[6:7]
	v_lshlrev_b64 v[16:17], 9, v[16:17]
	s_waitcnt lgkmcnt(0)
	v_max_f32_e32 v10, v0, v0
	v_lshl_add_u64 v[16:17], v[4:5], 0, v[16:17]
	v_bitop3_b32 v8, v8, s20, v8 bitop3:0x30
	v_cmp_eq_u32_e32 vcc, 0, v8
	v_max_f32_e32 v9, v1, v1
	v_max_f32_e32 v9, v10, v9
	v_cndmask_b32_e32 v9, v9, v0, vcc
	v_bcnt_u32_b32 v7, v8, 0
	v_max_f32_e32 v10, v9, v9
	v_max_f32_e32 v11, v2, v2
	v_max_f32_e32 v10, v10, v11
	v_cmp_lt_u32_e32 vcc, 1, v7
	v_max_f32_e32 v11, v3, v3
	s_nop 0
	v_cndmask_b32_e32 v9, v9, v10, vcc
	v_max_f32_e32 v10, v9, v9
	v_max_f32_e32 v18, v10, v11
	v_cmp_lt_u32_e32 vcc, 2, v7
	v_and_b32_e32 v10, 0xffff0000, v13
	v_lshlrev_b32_e32 v11, 16, v13
	v_cndmask_b32_e32 v19, v9, v18, vcc
	v_sub_f32_e32 v0, v0, v19
	v_exp_f32_e32 v0, v0
	v_cmp_ne_u32_e32 vcc, 0, v8
	v_and_b32_e32 v8, 0xffff0000, v12
	v_lshlrev_b32_e32 v9, 16, v12
	v_and_b32_e32 v12, 0xffff0000, v14
	v_lshlrev_b32_e32 v13, 16, v14
	v_and_b32_e32 v14, 0xffff0000, v15
	v_lshlrev_b32_e32 v15, 16, v15
	v_pk_mul_f32 v[8:9], v[0:1], v[8:9] op_sel_hi:[0,1]
	v_pk_mul_f32 v[10:11], v[0:1], v[10:11] op_sel_hi:[0,1]
	v_pk_mul_f32 v[12:13], v[0:1], v[12:13] op_sel_hi:[0,1]
	v_pk_mul_f32 v[14:15], v[0:1], v[14:15] op_sel_hi:[0,1]
	s_and_saveexec_b64 s[36:37], vcc
	s_cbranch_execz .LBB0_1069
	v_mov_b32_e32 v22, v230
	v_mov_b32_e32 v23, v231
	v_mov_b32_e32 v24, v232
	v_mov_b32_e32 v25, v233
	v_sub_f32_e32 v1, v1, v19
	v_exp_f32_e32 v26, v1
	v_and_b32_e32 v28, 0xffff0000, v22
	v_lshlrev_b32_e32 v29, 16, v22
	v_and_b32_e32 v22, 0xffff0000, v23
	v_lshlrev_b32_e32 v23, 16, v23
	v_pk_fma_f32 v[10:11], v[26:27], v[22:23], v[10:11] op_sel_hi:[0,1,1]
	v_and_b32_e32 v22, 0xffff0000, v24
	v_lshlrev_b32_e32 v23, 16, v24
	v_pk_fma_f32 v[12:13], v[26:27], v[22:23], v[12:13] op_sel_hi:[0,1,1]
	v_and_b32_e32 v22, 0xffff0000, v25
	v_lshlrev_b32_e32 v23, 16, v25
	v_add_f32_e32 v0, v0, v26
	v_pk_fma_f32 v[8:9], v[26:27], v[28:29], v[8:9] op_sel_hi:[0,1,1]
	v_pk_fma_f32 v[14:15], v[26:27], v[22:23], v[14:15] op_sel_hi:[0,1,1]
.LBB0_1069:
	s_or_b64 exec, exec, s[36:37]
	v_cmp_lt_u32_e32 vcc, 1, v7
	s_and_saveexec_b64 s[36:37], vcc
	s_cbranch_execz .LBB0_1071
	v_mov_b32_e32 v22, v234
	v_mov_b32_e32 v23, v235
	v_mov_b32_e32 v24, v236
	v_mov_b32_e32 v25, v237
	v_sub_f32_e32 v1, v2, v19
	v_exp_f32_e32 v2, v1
	v_and_b32_e32 v26, 0xffff0000, v22
	v_lshlrev_b32_e32 v27, 16, v22
	v_and_b32_e32 v22, 0xffff0000, v23
	v_lshlrev_b32_e32 v23, 16, v23
	v_pk_fma_f32 v[10:11], v[2:3], v[22:23], v[10:11] op_sel_hi:[0,1,1]
	v_and_b32_e32 v22, 0xffff0000, v24
	v_lshlrev_b32_e32 v23, 16, v24
	v_pk_fma_f32 v[12:13], v[2:3], v[22:23], v[12:13] op_sel_hi:[0,1,1]
	v_and_b32_e32 v22, 0xffff0000, v25
	v_lshlrev_b32_e32 v23, 16, v25
	v_add_f32_e32 v0, v2, v0
	v_pk_fma_f32 v[8:9], v[2:3], v[26:27], v[8:9] op_sel_hi:[0,1,1]
	v_pk_fma_f32 v[14:15], v[2:3], v[22:23], v[14:15] op_sel_hi:[0,1,1]
.LBB0_1071:
	s_or_b64 exec, exec, s[36:37]
	s_lshl_b32 s21, s19, 6
	s_not_b32 s19, s20
	v_cmp_lt_u32_e32 vcc, 2, v7
	s_and_saveexec_b64 s[36:37], vcc
	s_cbranch_execz .LBB0_1073
	v_sub_f32_e32 v1, v3, v18
	v_mov_b32_e32 v16, v246
	v_mov_b32_e32 v17, v247
	v_mov_b32_e32 v18, v248
	v_mov_b32_e32 v19, v249
	v_exp_f32_e32 v2, v1
	v_and_b32_e32 v22, 0xffff0000, v16
	v_lshlrev_b32_e32 v23, 16, v16
	v_and_b32_e32 v16, 0xffff0000, v17
	v_lshlrev_b32_e32 v17, 16, v17
	v_pk_fma_f32 v[10:11], v[2:3], v[16:17], v[10:11] op_sel_hi:[0,1,1]
	v_and_b32_e32 v16, 0xffff0000, v18
	v_lshlrev_b32_e32 v17, 16, v18
	v_pk_fma_f32 v[12:13], v[2:3], v[16:17], v[12:13] op_sel_hi:[0,1,1]
	v_and_b32_e32 v16, 0xffff0000, v19
	v_lshlrev_b32_e32 v17, 16, v19
	v_add_f32_e32 v0, v2, v0
	v_pk_fma_f32 v[8:9], v[2:3], v[22:23], v[8:9] op_sel_hi:[0,1,1]
	v_pk_fma_f32 v[14:15], v[2:3], v[16:17], v[14:15] op_sel_hi:[0,1,1]
.LBB0_1073:
	s_or_b64 exec, exec, s[36:37]
	s_ashr_i32 s20, s18, 31
	v_rcp_f32_e32 v16, v0
	s_add_u32 s10, s10, s18
	s_addc_u32 s11, s11, s20
	s_lshl_b64 s[10:11], s[10:11], 11
	s_add_u32 s10, s71, s10
	v_pk_mul_f32 v[0:1], v[16:17], v[8:9] op_sel_hi:[0,1]
	v_pk_mul_f32 v[2:3], v[16:17], v[10:11] op_sel_hi:[0,1]
	s_addc_u32 s11, s14, s11
	s_lshl_b32 s18, s21, 1
	v_pk_mov_b32 v[0:1], v[0:1], v[0:1] op_sel:[1,0]
	v_pk_mov_b32 v[2:3], v[2:3], v[2:3] op_sel:[1,0]
	s_add_u32 s10, s10, s18
	v_cvt_pk_bf16_f32 v0, v0, v1
	v_cvt_pk_bf16_f32 v1, v2, v3
	v_pk_mul_f32 v[2:3], v[16:17], v[12:13] op_sel_hi:[0,1]
	v_pk_mul_f32 v[8:9], v[16:17], v[14:15] op_sel_hi:[0,1]
	s_addc_u32 s11, s11, 0
	v_mov_b32_e32 v7, v177
	v_pk_mov_b32 v[2:3], v[2:3], v[2:3] op_sel:[1,0]
	v_pk_mov_b32 v[8:9], v[8:9], v[8:9] op_sel:[1,0]
	v_lshl_add_u64 v[6:7], s[10:11], 0, v[6:7]
	v_cvt_pk_bf16_f32 v2, v2, v3
	v_cvt_pk_bf16_f32 v3, v8, v9
	v_lshlrev_b32_e32 v8, 11, v176
	v_mov_b32_e32 v9, v177
	v_lshl_add_u64 v[8:9], v[6:7], 0, v[8:9]
	v_or_b32_e32 v22, 8, v176
	global_store_dwordx4 v[8:9], v[0:3], off
	v_or_b32_e32 v18, s8, v22
	v_mov_b32_e32 v19, s9
	v_lshl_add_u32 v0, v22, 7, v20
	ds_read_b128 v[26:29], v0 offset:51200
	v_lshl_add_u64 v[0:1], v[176:177], 0, s[12:13]
	v_lshl_add_u64 v[8:9], v[0:1], 2, s[38:39]
	v_mov_b32_e32 v0, v215
	v_and_b32_e32 v10, s19, v0
	v_lshl_add_u64 v[0:1], v[18:19], 4, s[28:29]
	v_mov_b32_e32 v0, v218
	v_mov_b32_e32 v1, v219
	v_mov_b32_e32 v2, v220
	v_mov_b32_e32 v3, v221
	ds_read_b32 v0, v21 offset:49184
	v_bcnt_u32_b32 v23, v10, 0
	v_cmp_ne_u32_e32 vcc, 0, v10
	v_cmp_eq_u32_e64 s[38:39], 0, v10
	v_lshlrev_b64 v[18:19], 9, v[18:19]
	s_waitcnt lgkmcnt(0)
	v_max_f32_e32 v11, v0, v0
	v_lshl_add_u64 v[18:19], v[4:5], 0, v[18:19]
	v_max_f32_e32 v10, v1, v1
	v_max_f32_e32 v10, v11, v10
	v_cndmask_b32_e64 v10, v10, v0, s[38:39]
	v_max_f32_e32 v11, v10, v10
	v_max_f32_e32 v12, v2, v2
	v_cmp_lt_u32_e64 s[38:39], 1, v23
	v_max_f32_e32 v11, v11, v12
	v_max_f32_e32 v12, v3, v3
	v_cndmask_b32_e64 v10, v10, v11, s[38:39]
	v_max_f32_e32 v11, v10, v10
	v_cmp_lt_u32_e64 s[38:39], 2, v23
	v_max_f32_e32 v24, v11, v12
	v_lshlrev_b32_e32 v11, 16, v26
	v_cndmask_b32_e64 v25, v10, v24, s[38:39]
	v_sub_f32_e32 v0, v0, v25
	v_exp_f32_e32 v0, v0
	v_and_b32_e32 v10, 0xffff0000, v26
	v_pk_mul_f32 v[16:17], v[0:1], v[10:11] op_sel_hi:[0,1]
	v_and_b32_e32 v10, 0xffff0000, v27
	v_lshlrev_b32_e32 v11, 16, v27
	v_pk_mul_f32 v[14:15], v[0:1], v[10:11] op_sel_hi:[0,1]
	v_and_b32_e32 v10, 0xffff0000, v28
	v_lshlrev_b32_e32 v11, 16, v28
	v_pk_mul_f32 v[12:13], v[0:1], v[10:11] op_sel_hi:[0,1]
	v_and_b32_e32 v10, 0xffff0000, v29
	v_lshlrev_b32_e32 v11, 16, v29
	v_pk_mul_f32 v[10:11], v[0:1], v[10:11] op_sel_hi:[0,1]
	s_and_saveexec_b64 s[10:11], vcc
	s_cbranch_execnz .LBB0_1084
	s_or_b64 exec, exec, s[10:11]
	v_cmp_lt_u32_e32 vcc, 1, v23
	s_and_saveexec_b64 s[10:11], vcc
	s_cbranch_execnz .LBB0_1085

; __device__ __forceinline__ unsigned cvtpk_s(float lo,float hi){f32x2_t v={lo,hi};bf16x2_t b=__builtin_convertvector(v,bf16x2_t);return __builtin_bit_cast(unsigned,b);}
; template<int THRL,int KIND> __device__ __forceinline__ void attn_unit(const bf16*Qlane,const bf16*__restrict__ Kh,const bf16*__restrict__ Vh,const int NT,const int NTs,char*shm,const float*cbh,const unsigned selw_in,const float*relb,const int h,bf16*Odirect,const int pidx,bf16*PO,float*PL,const int ...
;     ...
;     for(int i=0;i<4;++i){const int row=i*8+(lane>>3),ch=lane&7; const u32x4 v=*(const u32x4*)(stg+row*64+ch*8);
;       if constexpr(KIND==0){ ATTN_STORE16(Odirect+(long)row*DM+ch*8,v); }
;       else if constexpr(KIND==2){ const int d_=dstt[row]; if(d_>=0) ATTN_STORE16(PO+(long)d_*64+ch*8,v); }
;       else { const long ridx=(long)pidx+wid*32+row; const unsigned sm_=((const unsigned*)cbh)[wid*32+row]; const int np=__builtin_popcount(sm_&~(1u<<trel));
;         const f32x4v l4=*(const f32x4v*)(PL+ridx*4); const float l0=wsf[row];
;         float mx=l0; if(np>0)mx=__builtin_fmaxf(mx,l4[1]); if(np>1)mx=__builtin_fmaxf(mx,l4[2]); if(np>2)mx=__builtin_fmaxf(mx,l4[3]);
;         const float w0=__builtin_amdgcn_exp2f(l0-mx); float wsum=w0; float ac[8];
;         ac[0]=w0*__uint_as_float(v[0]<<16); ac[1]=w0*__uint_as_float(v[0]&0xffff0000u); ac[2]=w0*__uint_as_float(v[1]<<16); ac[3]=w0*__uint_as_float(v[1]&0xffff0000u);
;         ac[4]=w0*__uint_as_float(v[2]<<16); ac[5]=w0*__uint_as_float(v[2]&0xffff0000u); ac[6]=w0*__uint_as_float(v[3]<<16); ac[7]=w0*__uint_as_float(v[3]&0xffff0000u);
;         #pragma unroll
;         for(int s_=1;s_<4;++s_) if(s_<=np){ const float ws_=__builtin_amdgcn_exp2f(l4[s_]-mx); wsum+=ws_; const u32x4 p=*(const u32x4*)(PO+(ridx*4+s_)*64+ch*8);
;           ac[0]+=ws_*__uint_as_float(p[0]<<16); ac[1]+=ws_*__uint_as_float(p[0]&0xffff0000u); ac[2]+=ws_*__uint_as_float(p[1]<<16); ac[3]+=ws_*__uint_as_float(p[1]&0xffff0000u);
;           ac[4]+=ws_*__uint_as_float(p[2]<<16); ac[5]+=ws_*__uint_as_float(p[2]&0xffff0000u); ac[6]+=ws_*__uint_as_float(p[3]<<16); ac[7]+=ws_*__uint_as_float(p[3]&0xffff0000u); }
;         const float inv=__builtin_amdgcn_rcpf(wsum); u32x4 ov; ov[0]=cvtpk_s(ac[0]*inv,ac[1]*inv); ov[1]=cvtpk_s(ac[2]*inv,ac[3]*inv); ov[2]=cvtpk_s(ac[4]*inv,ac[5]*inv); ov[3]=cvtpk_s(ac[6]*inv,ac[7]*inv);
;         ATTN_STORE16(Odirect+(long)row*DM+ch*8,ov); } } }
.LBB0_1076:
	v_sub_f32_e32 v1, v3, v24
	v_mov_b32_e32 v24, v120
	v_mov_b32_e32 v25, v121
	v_mov_b32_e32 v26, v122
	v_mov_b32_e32 v27, v123
	v_exp_f32_e32 v2, v1
	v_and_b32_e32 v18, 0xffff0000, v24
	v_lshlrev_b32_e32 v19, 16, v24
	v_pk_fma_f32 v[16:17], v[2:3], v[18:19], v[16:17] op_sel_hi:[0,1,1]
	v_and_b32_e32 v18, 0xffff0000, v25
	v_lshlrev_b32_e32 v19, 16, v25
	v_pk_fma_f32 v[14:15], v[2:3], v[18:19], v[14:15] op_sel_hi:[0,1,1]
	v_and_b32_e32 v18, 0xffff0000, v26
	v_lshlrev_b32_e32 v19, 16, v26
	v_pk_fma_f32 v[12:13], v[2:3], v[18:19], v[12:13] op_sel_hi:[0,1,1]
	v_and_b32_e32 v18, 0xffff0000, v27
	v_lshlrev_b32_e32 v19, 16, v27
	v_add_f32_e32 v0, v2, v0
	v_pk_fma_f32 v[10:11], v[2:3], v[18:19], v[10:11] op_sel_hi:[0,1,1]
.LBB0_1077:
	s_or_b64 exec, exec, s[10:11]
	v_rcp_f32_e32 v18, v0
	s_nop 0
	v_pk_mul_f32 v[0:1], v[18:19], v[16:17] op_sel_hi:[0,1]
	v_pk_mul_f32 v[2:3], v[18:19], v[14:15] op_sel_hi:[0,1]
	v_pk_mov_b32 v[0:1], v[0:1], v[0:1] op_sel:[1,0]
	v_pk_mov_b32 v[2:3], v[2:3], v[2:3] op_sel:[1,0]
	v_cvt_pk_bf16_f32 v0, v0, v1
	v_cvt_pk_bf16_f32 v1, v2, v3
	v_pk_mul_f32 v[2:3], v[18:19], v[12:13] op_sel_hi:[0,1]
	v_pk_mul_f32 v[10:11], v[18:19], v[10:11] op_sel_hi:[0,1]
	v_pk_mov_b32 v[2:3], v[2:3], v[2:3] op_sel:[1,0]
	v_pk_mov_b32 v[10:11], v[10:11], v[10:11] op_sel:[1,0]
	v_cvt_pk_bf16_f32 v2, v2, v3
	v_cvt_pk_bf16_f32 v3, v10, v11
	v_lshlrev_b32_e32 v10, 11, v22
	v_mov_b32_e32 v11, v177
	v_or_b32_e32 v22, 16, v176
	v_lshl_add_u64 v[10:11], v[6:7], 0, v[10:11]
	v_or_b32_e32 v14, s8, v22
	v_mov_b32_e32 v15, s9
	global_store_dwordx4 v[10:11], v[0:3], off
	v_mov_b32_e32 v16, v216
	v_lshl_add_u32 v10, v22, 7, v20
	v_lshl_add_u64 v[0:1], v[14:15], 4, s[28:29]
	v_mov_b32_e32 v0, v222
	v_mov_b32_e32 v1, v223
	v_mov_b32_e32 v2, v224
	v_mov_b32_e32 v3, v225
	ds_read_b32 v0, v21 offset:49216
	ds_read_b128 v[10:13], v10 offset:51200
	v_lshlrev_b64 v[18:19], 9, v[14:15]
	v_lshl_add_u64 v[18:19], v[4:5], 0, v[18:19]
	s_waitcnt lgkmcnt(1)
	v_max_f32_e32 v17, v0, v0
	s_waitcnt lgkmcnt(0)
	v_and_b32_e32 v26, 0xffff0000, v12
	v_lshlrev_b32_e32 v27, 16, v12
	v_and_b32_e32 v14, 0xffff0000, v10
	v_lshlrev_b32_e32 v15, 16, v10
	v_and_b32_e32 v10, 0xffff0000, v11
	v_lshlrev_b32_e32 v11, 16, v11
	v_and_b32_e32 v28, 0xffff0000, v13
	v_lshlrev_b32_e32 v29, 16, v13
	v_and_b32_e32 v12, s19, v16
	v_cmp_eq_u32_e32 vcc, 0, v12
	v_bcnt_u32_b32 v24, v12, 0
	v_max_f32_e32 v16, v1, v1
	v_max_f32_e32 v16, v17, v16
	v_cndmask_b32_e32 v16, v16, v0, vcc
	v_max_f32_e32 v23, v2, v2
	v_max_f32_e32 v17, v16, v16
	v_max_f32_e32 v17, v17, v23
	v_cmp_lt_u32_e32 vcc, 1, v24
	v_max_f32_e32 v25, v3, v3
	s_nop 0
	v_cndmask_b32_e32 v16, v16, v17, vcc
	v_max_f32_e32 v17, v16, v16
	v_max_f32_e32 v23, v17, v25
	v_cmp_lt_u32_e32 vcc, 2, v24
	s_nop 1
	v_cndmask_b32_e32 v25, v16, v23, vcc
	v_sub_f32_e32 v0, v0, v25
	v_exp_f32_e32 v0, v0
	v_cmp_ne_u32_e32 vcc, 0, v12
	v_pk_mul_f32 v[16:17], v[0:1], v[14:15] op_sel_hi:[0,1]
	v_pk_mul_f32 v[14:15], v[0:1], v[10:11] op_sel_hi:[0,1]
	v_pk_mul_f32 v[12:13], v[0:1], v[26:27] op_sel_hi:[0,1]
	v_pk_mul_f32 v[10:11], v[0:1], v[28:29] op_sel_hi:[0,1]
	s_and_saveexec_b64 s[10:11], vcc
	s_cbranch_execnz .LBB0_1086
	s_or_b64 exec, exec, s[10:11]
	v_cmp_lt_u32_e32 vcc, 1, v24
	s_and_saveexec_b64 s[10:11], vcc
	s_cbranch_execnz .LBB0_1087

; __device__ __forceinline__ unsigned cvtpk_s(float lo,float hi){f32x2_t v={lo,hi};bf16x2_t b=__builtin_convertvector(v,bf16x2_t);return __builtin_bit_cast(unsigned,b);}
; template<int THRL,int KIND> __device__ __forceinline__ void attn_unit(const bf16*Qlane,const bf16*__restrict__ Kh,const bf16*__restrict__ Vh,const int NT,const int NTs,char*shm,const float*cbh,const unsigned selw_in,const float*relb,const int h,bf16*Odirect,const int pidx,bf16*PO,float*PL,const int ...
;     ...
;     for(int i=0;i<4;++i){const int row=i*8+(lane>>3),ch=lane&7; const u32x4 v=*(const u32x4*)(stg+row*64+ch*8);
;       if constexpr(KIND==0){ ATTN_STORE16(Odirect+(long)row*DM+ch*8,v); }
;       else if constexpr(KIND==2){ const int d_=dstt[row]; if(d_>=0) ATTN_STORE16(PO+(long)d_*64+ch*8,v); }
;       else { const long ridx=(long)pidx+wid*32+row; const unsigned sm_=((const unsigned*)cbh)[wid*32+row]; const int np=__builtin_popcount(sm_&~(1u<<trel));
;         const f32x4v l4=*(const f32x4v*)(PL+ridx*4); const float l0=wsf[row];
;         float mx=l0; if(np>0)mx=__builtin_fmaxf(mx,l4[1]); if(np>1)mx=__builtin_fmaxf(mx,l4[2]); if(np>2)mx=__builtin_fmaxf(mx,l4[3]);
;         const float w0=__builtin_amdgcn_exp2f(l0-mx); float wsum=w0; float ac[8];
;         ac[0]=w0*__uint_as_float(v[0]<<16); ac[1]=w0*__uint_as_float(v[0]&0xffff0000u); ac[2]=w0*__uint_as_float(v[1]<<16); ac[3]=w0*__uint_as_float(v[1]&0xffff0000u);
;         ac[4]=w0*__uint_as_float(v[2]<<16); ac[5]=w0*__uint_as_float(v[2]&0xffff0000u); ac[6]=w0*__uint_as_float(v[3]<<16); ac[7]=w0*__uint_as_float(v[3]&0xffff0000u);
;         #pragma unroll
;         for(int s_=1;s_<4;++s_) if(s_<=np){ const float ws_=__builtin_amdgcn_exp2f(l4[s_]-mx); wsum+=ws_; const u32x4 p=*(const u32x4*)(PO+(ridx*4+s_)*64+ch*8);
;           ac[0]+=ws_*__uint_as_float(p[0]<<16); ac[1]+=ws_*__uint_as_float(p[0]&0xffff0000u); ac[2]+=ws_*__uint_as_float(p[1]<<16); ac[3]+=ws_*__uint_as_float(p[1]&0xffff0000u);
;           ac[4]+=ws_*__uint_as_float(p[2]<<16); ac[5]+=ws_*__uint_as_float(p[2]&0xffff0000u); ac[6]+=ws_*__uint_as_float(p[3]<<16); ac[7]+=ws_*__uint_as_float(p[3]&0xffff0000u); }
;         const float inv=__builtin_amdgcn_rcpf(wsum); u32x4 ov; ov[0]=cvtpk_s(ac[0]*inv,ac[1]*inv); ov[1]=cvtpk_s(ac[2]*inv,ac[3]*inv); ov[2]=cvtpk_s(ac[4]*inv,ac[5]*inv); ov[3]=cvtpk_s(ac[6]*inv,ac[7]*inv);
;         ATTN_STORE16(Odirect+(long)row*DM+ch*8,ov); } } }
.LBB0_1080:
	v_mov_b32_e32 v24, v136
	v_mov_b32_e32 v25, v137
	v_mov_b32_e32 v26, v138
	v_mov_b32_e32 v27, v139
	v_sub_f32_e32 v1, v3, v23
	v_exp_f32_e32 v2, v1
	v_and_b32_e32 v18, 0xffff0000, v24
	v_lshlrev_b32_e32 v19, 16, v24
	v_pk_fma_f32 v[16:17], v[2:3], v[18:19], v[16:17] op_sel_hi:[0,1,1]
	v_and_b32_e32 v18, 0xffff0000, v25
	v_lshlrev_b32_e32 v19, 16, v25
	v_pk_fma_f32 v[14:15], v[2:3], v[18:19], v[14:15] op_sel_hi:[0,1,1]
	v_and_b32_e32 v18, 0xffff0000, v26
	v_lshlrev_b32_e32 v19, 16, v26
	v_pk_fma_f32 v[12:13], v[2:3], v[18:19], v[12:13] op_sel_hi:[0,1,1]
	v_and_b32_e32 v18, 0xffff0000, v27
	v_lshlrev_b32_e32 v19, 16, v27
	v_add_f32_e32 v0, v2, v0
	v_pk_fma_f32 v[10:11], v[2:3], v[18:19], v[10:11] op_sel_hi:[0,1,1]
.LBB0_1081:
	s_or_b64 exec, exec, s[10:11]
	v_rcp_f32_e32 v18, v0
	s_nop 0
	v_pk_mul_f32 v[0:1], v[18:19], v[16:17] op_sel_hi:[0,1]
	v_pk_mul_f32 v[2:3], v[18:19], v[14:15] op_sel_hi:[0,1]
	v_pk_mov_b32 v[0:1], v[0:1], v[0:1] op_sel:[1,0]
	v_pk_mov_b32 v[2:3], v[2:3], v[2:3] op_sel:[1,0]
	v_cvt_pk_bf16_f32 v0, v0, v1
	v_cvt_pk_bf16_f32 v1, v2, v3
	v_pk_mul_f32 v[2:3], v[18:19], v[12:13] op_sel_hi:[0,1]
	v_pk_mul_f32 v[10:11], v[18:19], v[10:11] op_sel_hi:[0,1]
	v_pk_mov_b32 v[2:3], v[2:3], v[2:3] op_sel:[1,0]
	v_pk_mov_b32 v[10:11], v[10:11], v[10:11] op_sel:[1,0]
	v_cvt_pk_bf16_f32 v2, v2, v3
	v_cvt_pk_bf16_f32 v3, v10, v11
	v_lshlrev_b32_e32 v10, 11, v22
	v_mov_b32_e32 v11, v177
	v_or_b32_e32 v16, 24, v176
	v_lshl_add_u64 v[10:11], v[6:7], 0, v[10:11]
	v_or_b32_e32 v12, s8, v16
	v_mov_b32_e32 v13, s9
	global_store_dwordx4 v[10:11], v[0:3], off
	v_mov_b32_e32 v14, v217
	s_nop 0
	v_lshl_add_u64 v[0:1], v[12:13], 4, s[28:29]
	v_mov_b32_e32 v0, v226
	v_mov_b32_e32 v1, v227
	v_mov_b32_e32 v2, v228
	v_mov_b32_e32 v3, v229
	v_lshl_add_u32 v8, v16, 7, v20
	ds_read_b32 v0, v21 offset:49248
	ds_read_b128 v[8:11], v8 offset:51200
	v_lshlrev_b64 v[20:21], 9, v[12:13]
	v_lshl_add_u64 v[4:5], v[4:5], 0, v[20:21]
	s_waitcnt lgkmcnt(1)
	v_max_f32_e32 v15, v0, v0
	s_waitcnt lgkmcnt(0)
	v_and_b32_e32 v22, 0xffff0000, v10
	v_lshlrev_b32_e32 v23, 16, v10
	v_and_b32_e32 v12, 0xffff0000, v8
	v_lshlrev_b32_e32 v13, 16, v8
	v_and_b32_e32 v8, 0xffff0000, v9
	v_lshlrev_b32_e32 v9, 16, v9
	v_and_b32_e32 v24, 0xffff0000, v11
	v_lshlrev_b32_e32 v25, 16, v11
	v_and_b32_e32 v10, s19, v14
	v_cmp_eq_u32_e32 vcc, 0, v10
	v_bcnt_u32_b32 v18, v10, 0
	v_max_f32_e32 v14, v1, v1
	v_max_f32_e32 v14, v15, v14
	v_cndmask_b32_e32 v14, v14, v0, vcc
	v_max_f32_e32 v17, v2, v2
	v_max_f32_e32 v15, v14, v14
	v_max_f32_e32 v15, v15, v17
	v_cmp_lt_u32_e32 vcc, 1, v18
	v_max_f32_e32 v19, v3, v3
	s_nop 0
	v_cndmask_b32_e32 v14, v14, v15, vcc
	v_max_f32_e32 v15, v14, v14
	v_max_f32_e32 v17, v15, v19
	v_cmp_lt_u32_e32 vcc, 2, v18
	s_nop 1
	v_cndmask_b32_e32 v19, v14, v17, vcc
	v_sub_f32_e32 v0, v0, v19
	v_exp_f32_e32 v0, v0
	v_cmp_ne_u32_e32 vcc, 0, v10
	v_pk_mul_f32 v[14:15], v[0:1], v[12:13] op_sel_hi:[0,1]
	v_pk_mul_f32 v[12:13], v[0:1], v[8:9] op_sel_hi:[0,1]
	v_pk_mul_f32 v[10:11], v[0:1], v[22:23] op_sel_hi:[0,1]
	v_pk_mul_f32 v[8:9], v[0:1], v[24:25] op_sel_hi:[0,1]
	s_and_saveexec_b64 s[10:11], vcc
	s_cbranch_execnz .LBB0_1088
	s_or_b64 exec, exec, s[10:11]
	v_cmp_lt_u32_e32 vcc, 1, v18
	s_and_saveexec_b64 s[10:11], vcc
	s_cbranch_execnz .LBB0_1089

; template<int THRL,int KIND> __device__ __forceinline__ void attn_unit(const bf16*Qlane,const bf16*__restrict__ Kh,const bf16*__restrict__ Vh,const int NT,const int NTs,char*shm,const float*cbh,const unsigned selw_in,const float*relb,const int h,bf16*Odirect,const int pidx,bf16*PO,float*PL,const int ...
;     ...
;         for(int s_=1;s_<4;++s_) if(s_<=np){ const float ws_=__builtin_amdgcn_exp2f(l4[s_]-mx); wsum+=ws_; const u32x4 p=*(const u32x4*)(PO+(ridx*4+s_)*64+ch*8);
;           ac[0]+=ws_*__uint_as_float(p[0]<<16); ac[1]+=ws_*__uint_as_float(p[0]&0xffff0000u); ac[2]+=ws_*__uint_as_float(p[1]<<16); ac[3]+=ws_*__uint_as_float(p[1]&0xffff0000u);
;           ac[4]+=ws_*__uint_as_float(p[2]<<16); ac[5]+=ws_*__uint_as_float(p[2]&0xffff0000u); ac[6]+=ws_*__uint_as_float(p[3]<<16); ac[7]+=ws_*__uint_as_float(p[3]&0xffff0000u); }
.LBB0_1084:
	v_mov_b32_e32 v26, v96
	v_mov_b32_e32 v27, v97
	v_mov_b32_e32 v28, v98
	v_mov_b32_e32 v29, v99
	v_sub_f32_e32 v1, v1, v25
	v_exp_f32_e32 v30, v1
	v_and_b32_e32 v32, 0xffff0000, v26
	v_lshlrev_b32_e32 v33, 16, v26
	v_and_b32_e32 v26, 0xffff0000, v27
	v_lshlrev_b32_e32 v27, 16, v27
	v_pk_fma_f32 v[14:15], v[30:31], v[26:27], v[14:15] op_sel_hi:[0,1,1]
	v_and_b32_e32 v26, 0xffff0000, v28
	v_lshlrev_b32_e32 v27, 16, v28
	v_pk_fma_f32 v[12:13], v[30:31], v[26:27], v[12:13] op_sel_hi:[0,1,1]
	v_and_b32_e32 v26, 0xffff0000, v29
	v_lshlrev_b32_e32 v27, 16, v29
	v_add_f32_e32 v0, v0, v30
	v_pk_fma_f32 v[16:17], v[30:31], v[32:33], v[16:17] op_sel_hi:[0,1,1]
	v_pk_fma_f32 v[10:11], v[30:31], v[26:27], v[10:11] op_sel_hi:[0,1,1]
	s_or_b64 exec, exec, s[10:11]
	v_cmp_lt_u32_e32 vcc, 1, v23
	s_and_saveexec_b64 s[10:11], vcc
	s_cbranch_execz .LBB0_1075
.LBB0_1085:
	v_mov_b32_e32 v26, v116
	v_mov_b32_e32 v27, v117
	v_mov_b32_e32 v28, v118
	v_mov_b32_e32 v29, v119
	v_sub_f32_e32 v1, v2, v25
	v_exp_f32_e32 v2, v1
	v_and_b32_e32 v30, 0xffff0000, v26
	v_lshlrev_b32_e32 v31, 16, v26
	v_and_b32_e32 v26, 0xffff0000, v27
	v_lshlrev_b32_e32 v27, 16, v27
	v_pk_fma_f32 v[14:15], v[2:3], v[26:27], v[14:15] op_sel_hi:[0,1,1]
	v_and_b32_e32 v26, 0xffff0000, v28
	v_lshlrev_b32_e32 v27, 16, v28
	v_pk_fma_f32 v[12:13], v[2:3], v[26:27], v[12:13] op_sel_hi:[0,1,1]
	v_and_b32_e32 v26, 0xffff0000, v29
	v_lshlrev_b32_e32 v27, 16, v29
	v_add_f32_e32 v0, v2, v0
	v_pk_fma_f32 v[16:17], v[2:3], v[30:31], v[16:17] op_sel_hi:[0,1,1]
	v_pk_fma_f32 v[10:11], v[2:3], v[26:27], v[10:11] op_sel_hi:[0,1,1]
	s_or_b64 exec, exec, s[10:11]
	v_cmp_lt_u32_e32 vcc, 2, v23
	s_and_saveexec_b64 s[10:11], vcc
	s_cbranch_execnz .LBB0_1076
	s_branch .LBB0_1077
.LBB0_1086:
	v_mov_b32_e32 v26, v124
	v_mov_b32_e32 v27, v125
	v_mov_b32_e32 v28, v126
	v_mov_b32_e32 v29, v127
	v_sub_f32_e32 v1, v1, v25
	v_exp_f32_e32 v30, v1
	v_and_b32_e32 v32, 0xffff0000, v26
	v_lshlrev_b32_e32 v33, 16, v26
	v_and_b32_e32 v26, 0xffff0000, v27
	v_lshlrev_b32_e32 v27, 16, v27
	v_pk_fma_f32 v[14:15], v[30:31], v[26:27], v[14:15] op_sel_hi:[0,1,1]
	v_and_b32_e32 v26, 0xffff0000, v28
	v_lshlrev_b32_e32 v27, 16, v28
	v_pk_fma_f32 v[12:13], v[30:31], v[26:27], v[12:13] op_sel_hi:[0,1,1]
	v_and_b32_e32 v26, 0xffff0000, v29
	v_lshlrev_b32_e32 v27, 16, v29
	v_add_f32_e32 v0, v0, v30
	v_pk_fma_f32 v[16:17], v[30:31], v[32:33], v[16:17] op_sel_hi:[0,1,1]
	v_pk_fma_f32 v[10:11], v[30:31], v[26:27], v[10:11] op_sel_hi:[0,1,1]
	s_or_b64 exec, exec, s[10:11]
	v_cmp_lt_u32_e32 vcc, 1, v24
	s_and_saveexec_b64 s[10:11], vcc
	s_cbranch_execz .LBB0_1079
.LBB0_1087:
	v_mov_b32_e32 v26, v128
	v_mov_b32_e32 v27, v129
	v_mov_b32_e32 v28, v130
	v_mov_b32_e32 v29, v131
	v_sub_f32_e32 v1, v2, v25
	v_exp_f32_e32 v2, v1
	v_and_b32_e32 v30, 0xffff0000, v26
	v_lshlrev_b32_e32 v31, 16, v26
	v_and_b32_e32 v26, 0xffff0000, v27
	v_lshlrev_b32_e32 v27, 16, v27
	v_pk_fma_f32 v[14:15], v[2:3], v[26:27], v[14:15] op_sel_hi:[0,1,1]
	v_and_b32_e32 v26, 0xffff0000, v28
	v_lshlrev_b32_e32 v27, 16, v28
	v_pk_fma_f32 v[12:13], v[2:3], v[26:27], v[12:13] op_sel_hi:[0,1,1]
	v_and_b32_e32 v26, 0xffff0000, v29
	v_lshlrev_b32_e32 v27, 16, v29
	v_add_f32_e32 v0, v2, v0
	v_pk_fma_f32 v[16:17], v[2:3], v[30:31], v[16:17] op_sel_hi:[0,1,1]
	v_pk_fma_f32 v[10:11], v[2:3], v[26:27], v[10:11] op_sel_hi:[0,1,1]
	s_or_b64 exec, exec, s[10:11]
	v_cmp_lt_u32_e32 vcc, 2, v24
	s_and_saveexec_b64 s[10:11], vcc
	s_cbranch_execnz .LBB0_1080
	s_branch .LBB0_1081
.LBB0_1088:
	v_mov_b32_e32 v20, v140
	v_mov_b32_e32 v21, v141
	v_mov_b32_e32 v22, v142
	v_mov_b32_e32 v23, v143
	v_sub_f32_e32 v1, v1, v19
	v_exp_f32_e32 v24, v1
	v_and_b32_e32 v26, 0xffff0000, v20
	v_lshlrev_b32_e32 v27, 16, v20
	v_and_b32_e32 v20, 0xffff0000, v21
	v_lshlrev_b32_e32 v21, 16, v21
	v_pk_fma_f32 v[12:13], v[24:25], v[20:21], v[12:13] op_sel_hi:[0,1,1]
	v_and_b32_e32 v20, 0xffff0000, v22
	v_lshlrev_b32_e32 v21, 16, v22
	v_pk_fma_f32 v[10:11], v[24:25], v[20:21], v[10:11] op_sel_hi:[0,1,1]
	v_and_b32_e32 v20, 0xffff0000, v23
	v_lshlrev_b32_e32 v21, 16, v23
	v_add_f32_e32 v0, v0, v24
	v_pk_fma_f32 v[14:15], v[24:25], v[26:27], v[14:15] op_sel_hi:[0,1,1]
	v_pk_fma_f32 v[8:9], v[24:25], v[20:21], v[8:9] op_sel_hi:[0,1,1]
	s_or_b64 exec, exec, s[10:11]
	v_cmp_lt_u32_e32 vcc, 1, v18
	s_and_saveexec_b64 s[10:11], vcc
	s_cbranch_execz .LBB0_1083
.LBB0_1089:
	v_mov_b32_e32 v20, v144
	v_mov_b32_e32 v21, v145
	v_mov_b32_e32 v22, v146
	v_mov_b32_e32 v23, v147
	v_sub_f32_e32 v1, v2, v19
	v_exp_f32_e32 v2, v1
	v_and_b32_e32 v24, 0xffff0000, v20
	v_lshlrev_b32_e32 v25, 16, v20
	v_and_b32_e32 v20, 0xffff0000, v21
	v_lshlrev_b32_e32 v21, 16, v21
	v_pk_fma_f32 v[12:13], v[2:3], v[20:21], v[12:13] op_sel_hi:[0,1,1]
	v_and_b32_e32 v20, 0xffff0000, v22
	v_lshlrev_b32_e32 v21, 16, v22
	v_pk_fma_f32 v[10:11], v[2:3], v[20:21], v[10:11] op_sel_hi:[0,1,1]
	v_and_b32_e32 v20, 0xffff0000, v23
	v_lshlrev_b32_e32 v21, 16, v23
	v_add_f32_e32 v0, v2, v0
	v_pk_fma_f32 v[14:15], v[2:3], v[24:25], v[14:15] op_sel_hi:[0,1,1]
	v_pk_fma_f32 v[8:9], v[2:3], v[20:21], v[8:9] op_sel_hi:[0,1,1]
	s_or_b64 exec, exec, s[10:11]
	v_cmp_lt_u32_e32 vcc, 2, v18
	s_and_saveexec_b64 s[10:11], vcc
	s_cbranch_execz .LBB0_923
.LBB0_1090:
	v_sub_f32_e32 v1, v3, v17
	v_mov_b32_e32 v2, v148
	v_mov_b32_e32 v3, v149
	v_mov_b32_e32 v4, v150
	v_mov_b32_e32 v5, v151
	v_exp_f32_e32 v18, v1
	v_and_b32_e32 v20, 0xffff0000, v2
	v_lshlrev_b32_e32 v21, 16, v2
	v_and_b32_e32 v2, 0xffff0000, v3
	v_lshlrev_b32_e32 v3, 16, v3
	v_pk_fma_f32 v[12:13], v[18:19], v[2:3], v[12:13] op_sel_hi:[0,1,1]
	v_and_b32_e32 v2, 0xffff0000, v4
	v_lshlrev_b32_e32 v3, 16, v4
	v_pk_fma_f32 v[10:11], v[18:19], v[2:3], v[10:11] op_sel_hi:[0,1,1]
	v_and_b32_e32 v2, 0xffff0000, v5
	v_lshlrev_b32_e32 v3, 16, v5
	v_add_f32_e32 v0, v18, v0
	v_pk_fma_f32 v[14:15], v[18:19], v[20:21], v[14:15] op_sel_hi:[0,1,1]
	v_pk_fma_f32 v[8:9], v[18:19], v[2:3], v[8:9] op_sel_hi:[0,1,1]
	s_branch .LBB0_923
